# attention unit epilogue: 8 norm-weight loads + lambda load issued at key-loop exit (one wait), prologue Q wait counted vmcnt(12)
# speedup vs baseline: 1.0011x; 1.0011x over previous
.LBB0_1320:
	v_readfirstlane_b32 s67, v107
	s_ashr_i32 s61, s67, 6
	s_lshl_b32 s66, s61, 4
	s_and_b32 s70, s66, 48
	v_or_b32_e32 v129, s70, v109
	v_mul_u32_u24_e32 v0, s49, v129
	s_ashr_i32 s23, s67, 8
	v_lshlrev_b32_e32 v0, 1, v0
	v_lshl_add_u64 v[2:3], s[30:31], 0, v[0:1]
	s_lshl_b32 s30, s23, 6
	s_ashr_i32 s31, s30, 31
	v_mul_lo_u32 v8, s49, v120
	v_lshl_add_u64 v[2:3], s[30:31], 1, v[2:3]
	s_lshl_b32 s31, s61, 10
	s_waitcnt vmcnt(0)
	v_mul_lo_u32 v10, s0, v122
	v_mov_b32_e32 v113, v1
	v_add_lshl_u32 v0, v8, v121, 1
	s_add_i32 s76, s2, s31
	v_lshl_add_u64 v[6:7], v[2:3], 0, v[112:113]
	v_add_lshl_u32 v8, v123, v10, 1
	v_lshl_add_u64 v[10:11], s[34:35], 0, v[0:1]
	s_mov_b32 m0, s76
	v_mul_lo_u32 v9, s0, v120
	global_load_dwordx4 v[2:5], v[6:7], off
	global_load_dwordx4 v[14:17], v[6:7], off offset:64
	s_barrier
	s_add_i32 s0, s76, 0xc000
	global_load_lds_dwordx4 v0, s[34:35]
	v_lshl_add_u64 v[10:11], v[10:11], 0, s[44:45]
	s_add_i32 m0, s76, 0x2000
	v_add_lshl_u32 v6, v9, v121, 1
	global_load_lds_dwordx4 v[10:11], off
	s_mov_b32 m0, s0
	s_add_i32 s0, s59, s31
	global_load_lds_dwordx4 v6, s[36:37]
	s_add_i32 m0, s76, 0xe000
	s_lshl_b32 s74, s49, 7
	global_load_lds_dwordx4 v8, s[36:37]
	s_add_i32 m0, s76, 0x4000
	s_add_u32 s50, s34, s74
	s_addc_u32 s51, s35, 0
	v_mov_b32_e32 v7, v1
	v_lshl_add_u64 v[18:19], s[50:51], 0, v[0:1]
	v_lshl_add_u64 v[10:11], s[36:37], 0, v[6:7]
	v_mov_b32_e32 v9, v1
	global_load_lds_dwordx4 v0, s[50:51]
	v_lshl_add_u64 v[18:19], v[18:19], 0, s[44:45]
	s_add_i32 m0, s76, 0x6000
	v_lshl_add_u64 v[12:13], s[36:37], 0, v[8:9]
	global_load_lds_dwordx4 v[18:19], off
	v_lshl_add_u64 v[18:19], v[10:11], 0, s[44:45]
	s_mov_b32 m0, s0
	s_mov_b32 s77, 1
	global_load_lds_dwordx4 v[18:19], off
	v_lshl_add_u64 v[18:19], v[12:13], 0, s[44:45]
	s_add_i32 m0, s0, 0x2000
	s_add_i32 s0, s60, s31
	global_load_lds_dwordx4 v[18:19], off
	s_add_i32 m0, s76, 0x8000
	s_add_u32 s50, s50, s74
	s_addc_u32 s51, s51, 0
	v_lshl_add_u64 v[18:19], s[50:51], 0, v[0:1]
	global_load_lds_dwordx4 v0, s[50:51]
	v_lshl_add_u64 v[18:19], v[18:19], 0, s[44:45]
	s_add_i32 m0, s76, 0xa000
	s_mov_b64 s[50:51], 0x100
	global_load_lds_dwordx4 v[18:19], off
	v_lshl_add_u64 v[10:11], v[10:11], 0, s[50:51]
	s_mov_b32 m0, s0
	s_nop 0
	global_load_lds_dwordx4 v[10:11], off
	v_lshl_add_u64 v[10:11], v[12:13], 0, s[50:51]
	s_add_i32 m0, s0, 0x2000
	s_nop 0
	global_load_lds_dwordx4 v[10:11], off
	s_waitcnt vmcnt(12)
	v_lshlrev_b32_e32 v10, 16, v2
	v_and_b32_e32 v11, 0xffff0000, v2
	s_mov_b32 s0, 0x3e38aa3b
	v_lshlrev_b32_e32 v2, 16, v3
	v_and_b32_e32 v3, 0xffff0000, v3
	v_pk_mul_f32 v[10:11], v[10:11], s[0:1] op_sel_hi:[1,0]
	v_pk_mul_f32 v[2:3], v[2:3], s[0:1] op_sel_hi:[1,0]
	v_cvt_pk_bf16_f32 v10, v10, v11
	v_cvt_pk_bf16_f32 v11, v2, v3
	v_lshlrev_b32_e32 v2, 16, v4
	v_and_b32_e32 v3, 0xffff0000, v4
	v_pk_mul_f32 v[2:3], v[2:3], s[0:1] op_sel_hi:[1,0]
	s_lshl_b32 s50, s23, 13
	v_cvt_pk_bf16_f32 v12, v2, v3
	v_lshlrev_b32_e32 v2, 16, v5
	v_and_b32_e32 v3, 0xffff0000, v5
	v_pk_mul_f32 v[2:3], v[2:3], s[0:1] op_sel_hi:[1,0]
	s_waitcnt vmcnt(8)
	s_barrier
	v_cvt_pk_bf16_f32 v13, v2, v3
	v_lshlrev_b32_e32 v2, 16, v14
	v_and_b32_e32 v3, 0xffff0000, v14
	v_pk_mul_f32 v[2:3], v[2:3], s[0:1] op_sel_hi:[1,0]
	v_add_u32_e32 v34, s50, v124
	v_cvt_pk_bf16_f32 v18, v2, v3
	v_lshlrev_b32_e32 v2, 16, v15
	v_and_b32_e32 v3, 0xffff0000, v15
	v_pk_mul_f32 v[14:15], v[2:3], s[0:1] op_sel_hi:[1,0]
	ds_read_b128 v[2:5], v34
	ds_read_b128 v[22:25], v34 offset:1024
	v_cvt_pk_bf16_f32 v19, v14, v15
	v_lshlrev_b32_e32 v14, 16, v16
	v_and_b32_e32 v15, 0xffff0000, v16
	v_pk_mul_f32 v[14:15], v[14:15], s[0:1] op_sel_hi:[1,0]
	v_lshlrev_b32_e32 v26, 16, v17
	v_cvt_pk_bf16_f32 v20, v14, v15
	v_and_b32_e32 v27, 0xffff0000, v17
	s_waitcnt lgkmcnt(0)
	v_mfma_f32_16x16x32_bf16 v[2:5], v[2:5], v[10:13], 0
	ds_read_b128 v[14:17], v34 offset:2048
	v_pk_mul_f32 v[26:27], v[26:27], s[0:1] op_sel_hi:[1,0]
	ds_read_b128 v[30:33], v34 offset:6144
	v_cvt_pk_bf16_f32 v21, v26, v27
	ds_read_b128 v[26:29], v34 offset:4096
	s_waitcnt lgkmcnt(0)
	v_mfma_f32_16x16x32_bf16 v[30:33], v[30:33], v[10:13], 0
	s_add_i32 s0, s71, -2
	s_mulk_i32 s49, 0x180
	s_add_u32 s34, s34, s49
	v_mfma_f32_16x16x32_bf16 v[22:25], v[22:25], v[18:21], v[2:5]
	s_addc_u32 s35, s35, 0
	v_lshl_add_u64 v[114:115], s[34:35], 0, v[0:1]
	s_add_u32 s34, s36, 0x180
	ds_read_b128 v[2:5], v34 offset:3072
	v_mfma_f32_16x16x32_bf16 v[14:17], v[14:17], v[10:13], 0
	s_mov_b32 s88, s75
	s_mov_b32 s89, s75
	s_addc_u32 s35, s37, 0
	s_waitcnt lgkmcnt(0)
	v_mfma_f32_16x16x32_bf16 v[14:17], v[2:5], v[18:21], v[14:17]
	ds_read_b128 v[2:5], v34 offset:5120
	ds_read_b128 v[34:37], v34 offset:7168
	s_mov_b32 s90, s75
	v_mfma_f32_16x16x32_bf16 v[26:29], v[26:29], v[10:13], 0
	s_mov_b32 s91, s75
	v_lshl_add_u64 v[118:119], s[34:35], 0, v[6:7]
	v_mov_b32_e32 v6, 0
	s_waitcnt lgkmcnt(0)
	v_mfma_f32_16x16x32_bf16 v[26:29], v[2:5], v[18:21], v[26:29]
	v_mov_b64_e32 v[2:3], s[88:89]
	v_mov_b64_e32 v[4:5], s[90:91]
	v_lshl_add_u64 v[116:117], s[34:35], 0, v[8:9]
	v_mfma_f32_16x16x32_bf16 v[30:33], v[34:37], v[18:21], v[30:33]
	v_max_f32_e32 v34, v25, v25
	v_max_f32_e32 v35, v24, v24
	v_max_f32_e32 v34, v35, v34
	v_max_f32_e32 v35, v17, v17
	v_max_f32_e32 v36, v16, v16
	v_max_f32_e32 v35, v36, v35
	v_max_f32_e32 v36, v27, v27
	v_max_f32_e32 v37, v26, v26
	v_max_f32_e32 v36, v37, v36
	v_max_f32_e32 v37, v29, v29
	v_max_f32_e32 v38, v28, v28
	v_max_f32_e32 v37, v38, v37
	v_max_f32_e32 v38, v33, v33
	v_max_f32_e32 v39, v32, v32
	v_max_f32_e32 v38, v39, v38
	v_max3_f32 v38, v30, v31, v38
	v_max3_f32 v34, v22, v23, v34
	v_max3_f32 v35, v14, v15, v35
	v_max3_f32 v36, v36, v37, v38
	v_max3_f32 v34, v34, v35, v36
	v_mov_b32_e32 v35, v34
	s_nop 1
	v_permlane16_swap_b32_e32 v34, v35
	v_max_f32_e32 v35, v35, v35
	v_max_f32_e32 v34, v34, v34
	v_max_f32_e32 v34, v34, v35
	v_mov_b32_e32 v35, v34
	s_nop 1
	v_permlane32_swap_b32_e32 v34, v35
	v_max_f32_e32 v35, v35, v35
	v_max_f32_e32 v34, v34, v34
	v_max_f32_e32 v113, v34, v35
	v_sub_f32_e32 v74, v22, v113
	v_sub_f32_e32 v22, v26, v113
	v_sub_f32_e32 v26, v30, v113
	v_mov_b32_e32 v30, 0
	v_sub_f32_e32 v77, v25, v113
	v_sub_f32_e32 v76, v24, v113
	v_sub_f32_e32 v75, v23, v113
	v_sub_f32_e32 v73, v17, v113
	v_sub_f32_e32 v72, v16, v113
	v_sub_f32_e32 v71, v15, v113
	v_sub_f32_e32 v70, v14, v113
	v_sub_f32_e32 v25, v29, v113
	v_sub_f32_e32 v24, v28, v113
	v_sub_f32_e32 v23, v27, v113
	v_sub_f32_e32 v29, v33, v113
	v_sub_f32_e32 v28, v32, v113
	v_sub_f32_e32 v27, v31, v113
	v_add_u32_e32 v130, s50, v127
	s_mov_b32 s36, 0
	s_mov_b32 s37, 3
	s_mov_b32 s49, 0
	s_mov_b32 s72, 0
	s_mov_b32 s50, 0
	v_mov_b32_e32 v7, v6
	v_mov_b32_e32 v8, v6
	v_mov_b32_e32 v9, v6
	v_mov_b32_e32 v14, v6
	v_mov_b32_e32 v15, v6
	v_mov_b32_e32 v16, v6
	v_mov_b32_e32 v17, v6
	v_mov_b32_e32 v31, v30
	v_mov_b32_e32 v32, v30
	v_mov_b32_e32 v33, v30
	v_mov_b32_e32 v50, v30
	v_mov_b32_e32 v51, v30
	v_mov_b32_e32 v52, v30
	v_mov_b32_e32 v53, v30
	v_mov_b32_e32 v42, v30
	v_mov_b32_e32 v43, v30
	v_mov_b32_e32 v44, v30
	v_mov_b32_e32 v45, v30
	v_mov_b32_e32 v34, v30
	v_mov_b32_e32 v35, v30
	v_mov_b32_e32 v36, v30
	v_mov_b32_e32 v37, v30
	v_mov_b32_e32 v58, v30
	v_mov_b32_e32 v59, v30
	v_mov_b32_e32 v60, v30
	v_mov_b32_e32 v61, v30
	v_mov_b32_e32 v54, v30
	v_mov_b32_e32 v55, v30
	v_mov_b32_e32 v56, v30
	v_mov_b32_e32 v57, v30
	v_mov_b32_e32 v46, v30
	v_mov_b32_e32 v47, v30
	v_mov_b32_e32 v48, v30
	v_mov_b32_e32 v49, v30
	v_mov_b32_e32 v38, v30
	v_mov_b32_e32 v39, v30
	v_mov_b32_e32 v40, v30
	v_mov_b32_e32 v41, v30
	v_mov_b32_e32 v194, 0
	v_xor_b32_e32 v150, 0x80000000, v113
	v_mov_b32_e32 v154, s48
	v_mov_b32_e32 v151, v150
	v_mov_b32_e32 v155, v154
	v_mov_b32_e32 v152, v150
	v_mov_b32_e32 v156, v154
	v_mov_b32_e32 v153, v150
	v_mov_b32_e32 v157, v154
	s_lshl_b32 s51, s49, 14
	v_add_u32_e32 v131, s51, v124
	ds_read_b128 v[204:207], v131 offset:49152
	ds_read_b128 v[208:211], v131 offset:51200
	ds_read_b128 v[212:215], v131 offset:53248
	ds_read_b128 v[216:219], v131 offset:55296
	s_mov_b64 s[88:89], s[86:87]
	s_cmp_ge_u32 s50, s0
	s_mov_b64 s[34:35], -1
	s_cbranch_scc0 .LBB0_1322

.LBB0_1333:
	v_lshl_add_u32 v0, s72, 14, v124
	ds_read_b128 v[22:25], v0 offset:53248
	ds_read_b128 v[26:29], v0 offset:55296
	ds_read_b128 v[10:13], v0 offset:49152
	ds_read_b128 v[18:21], v0 offset:51200
	s_mov_b32 s49, s48
	s_mov_b32 s50, s48
	s_mov_b32 s51, s48
	s_cmp_lg_u64 s[28:29], 0
	s_waitcnt lgkmcnt(0)
	global_load_dwordx2 v[176:177], v1, s[18:19]
	global_load_dwordx4 v[160:163], v[110:111], off
	global_load_dwordx4 v[164:167], v[110:111], off offset:64
	global_load_dwordx4 v[168:171], v[110:111], off offset:128
	global_load_dwordx4 v[172:175], v[110:111], off offset:192
	global_load_dwordx4 v[204:207], v[110:111], off offset:256
	global_load_dwordx4 v[208:211], v[110:111], off offset:320
	global_load_dwordx4 v[212:215], v[110:111], off offset:384
	global_load_dwordx4 v[216:219], v[110:111], off offset:448
	v_mfma_f32_16x16x32_bf16 v[22:25], v[22:25], v[14:17], v[42:45]
	s_nop 2
	ds_read_b128 v[42:45], v0 offset:61440
	v_mfma_f32_16x16x32_bf16 v[26:29], v[26:29], v[14:17], v[34:37]
	s_nop 2
	ds_read_b128 v[34:37], v0 offset:59392
	s_waitcnt lgkmcnt(0)
	v_mfma_f32_16x16x32_bf16 v[42:45], v[42:45], v[14:17], v[46:49]
	s_nop 2
	ds_read_b128 v[46:49], v0 offset:63488
	s_waitcnt lgkmcnt(0)
	v_mfma_f32_16x16x32_bf16 v[46:49], v[46:49], v[14:17], v[38:41]
	s_nop 2
	ds_read_b128 v[38:41], v0 offset:50176
	v_mfma_f32_16x16x32_bf16 v[10:13], v[10:13], v[14:17], v[30:33]
	s_waitcnt lgkmcnt(0)
	v_mfma_f32_16x16x32_bf16 v[10:13], v[38:41], v[6:9], v[10:13]
	ds_read_b128 v[38:41], v0 offset:52224
	ds_read_b128 v[30:33], v0 offset:57344
	v_mfma_f32_16x16x32_bf16 v[18:21], v[18:21], v[14:17], v[50:53]
	s_waitcnt lgkmcnt(0)
	v_mfma_f32_16x16x32_bf16 v[18:21], v[38:41], v[6:9], v[18:21]
	ds_read_b128 v[38:41], v0 offset:54272
	s_waitcnt lgkmcnt(0)
	v_mfma_f32_16x16x32_bf16 v[22:25], v[38:41], v[6:9], v[22:25]
	ds_read_b128 v[38:41], v0 offset:56320
	s_waitcnt lgkmcnt(0)
	v_mfma_f32_16x16x32_bf16 v[26:29], v[38:41], v[6:9], v[26:29]
	ds_read_b128 v[38:41], v0 offset:58368
	v_mfma_f32_16x16x32_bf16 v[30:33], v[30:33], v[14:17], v[58:61]
	s_waitcnt lgkmcnt(0)
	v_mfma_f32_16x16x32_bf16 v[30:33], v[38:41], v[6:9], v[30:33]
	ds_read_b128 v[38:41], v0 offset:60416
	v_mfma_f32_16x16x32_bf16 v[34:37], v[34:37], v[14:17], v[54:57]
	s_waitcnt lgkmcnt(0)
	v_mfma_f32_16x16x32_bf16 v[34:37], v[38:41], v[6:9], v[34:37]
	ds_read_b128 v[38:41], v0 offset:62464
	s_waitcnt lgkmcnt(0)
	v_mfma_f32_16x16x32_bf16 v[38:41], v[38:41], v[6:9], v[42:45]
	s_nop 2
	ds_read_b128 v[42:45], v0 offset:64512
	s_waitcnt lgkmcnt(0)
	v_mfma_f32_16x16x32_bf16 v[42:45], v[42:45], v[6:9], v[46:49]
	s_nop 2
	v_mov_b64_e32 v[46:47], s[48:49]
	v_mov_b64_e32 v[48:49], s[50:51]
	s_nop 1
	v_mfma_f32_16x16x32_bf16 v[2:5], v[46:49], v[14:17], v[2:5]
	v_mfma_f32_16x16x32_bf16 v[2:5], v[46:49], v[6:9], v[2:5]
	s_cbranch_scc0 .LBB0_1337
	s_nop 6
	v_or_b32_e32 v4, s30, v129
	v_ashrrev_i32_e32 v5, 31, v4
	v_lshlrev_b64 v[4:5], 9, v[4:5]
	v_lshl_add_u64 v[4:5], s[28:29], 0, v[4:5]
	v_lshlrev_b32_e32 v0, 2, v106
	v_lshl_add_u64 v[4:5], v[4:5], 0, v[0:1]
	global_store_dwordx4 v[4:5], v[10:13], off
	global_store_dwordx4 v[4:5], v[18:21], off offset:64
	global_store_dwordx4 v[4:5], v[22:25], off offset:128
	global_store_dwordx4 v[4:5], v[26:29], off offset:192
	global_store_dwordx4 v[4:5], v[30:33], off offset:256
	global_store_dwordx4 v[4:5], v[34:37], off offset:320
	global_store_dwordx4 v[4:5], v[38:41], off offset:384
	global_store_dwordx4 v[4:5], v[42:45], off offset:448
	s_and_saveexec_b64 s[34:35], s[8:9]
	v_readlane_b32 s72, v255, 9
	v_readlane_b32 s73, v255, 10
	s_cbranch_execz .LBB0_1336
	s_add_i32 s0, s30, s70
	s_add_i32 s30, s0, 0x4000
	v_or_b32_e32 v4, s30, v109
	v_ashrrev_i32_e32 v5, 31, v4
	v_lshl_add_u64 v[4:5], v[4:5], 2, s[28:29]
	s_addk_i32 s0, 0x4080
	global_store_dword v[4:5], v113, off
	v_or_b32_e32 v4, s0, v109
	v_ashrrev_i32_e32 v5, 31, v4
	v_lshl_add_u64 v[4:5], v[4:5], 2, s[28:29]
	global_store_dword v[4:5], v2, off

.LBB0_1338:
	s_cmpk_lt_u32 s67, 0x100
	s_cselect_b64 s[26:27], -1, 0
	s_cmp_lg_u32 s23, 1
	s_waitcnt vmcnt(0)
	s_barrier
	v_cndmask_b32_e64 v0, v176, 1.0, s[26:27]
	v_div_scale_f32 v3, s[28:29], v2, v2, v0
	v_rcp_f32_e32 v4, v3
	v_div_scale_f32 v5, vcc, v0, v2, v0
	v_fma_f32 v6, -v3, v4, 1.0
	v_fmac_f32_e32 v4, v6, v4
	v_mul_f32_e32 v6, v5, v4
	v_fma_f32 v7, -v3, v6, v5
	v_fmac_f32_e32 v6, v7, v4
	v_fma_f32 v3, -v3, v6, v5
	v_div_fmas_f32 v3, v3, v4, v6
	v_div_fixup_f32 v0, v3, v2, v0
	v_pk_mul_f32 v[52:53], v[12:13], v[0:1] op_sel_hi:[1,0]
	v_pk_mul_f32 v[50:51], v[10:11], v[0:1] op_sel_hi:[1,0]
	v_pk_mul_f32 v[48:49], v[20:21], v[0:1] op_sel_hi:[1,0]
	v_pk_mul_f32 v[46:47], v[18:19], v[0:1] op_sel_hi:[1,0]
	v_pk_mul_f32 v[24:25], v[24:25], v[0:1] op_sel_hi:[1,0]
	v_pk_mul_f32 v[22:23], v[22:23], v[0:1] op_sel_hi:[1,0]
	v_pk_mul_f32 v[20:21], v[28:29], v[0:1] op_sel_hi:[1,0]
	v_pk_mul_f32 v[18:19], v[26:27], v[0:1] op_sel_hi:[1,0]
	v_pk_mul_f32 v[16:17], v[32:33], v[0:1] op_sel_hi:[1,0]
	v_pk_mul_f32 v[14:15], v[30:31], v[0:1] op_sel_hi:[1,0]
	v_pk_mul_f32 v[12:13], v[36:37], v[0:1] op_sel_hi:[1,0]
	v_pk_mul_f32 v[10:11], v[34:35], v[0:1] op_sel_hi:[1,0]
	v_pk_mul_f32 v[8:9], v[40:41], v[0:1] op_sel_hi:[1,0]
	v_pk_mul_f32 v[6:7], v[38:39], v[0:1] op_sel_hi:[1,0]
	v_pk_mul_f32 v[4:5], v[44:45], v[0:1] op_sel_hi:[1,0]
	v_pk_mul_f32 v[2:3], v[42:43], v[0:1] op_sel_hi:[1,0]
	s_cbranch_scc1 .LBB0_1340
	v_mad_u32_u24 v0, v129, s79, v108
	ds_write_b128 v0, v[50:53]
	ds_write_b128 v0, v[46:49] offset:64
	ds_write_b128 v0, v[22:25] offset:128
	ds_write_b128 v0, v[18:21] offset:192
	ds_write_b128 v0, v[14:17] offset:256
	ds_write_b128 v0, v[10:13] offset:320
	ds_write_b128 v0, v[6:9] offset:384
	ds_write_b128 v0, v[2:5] offset:448
.LBB0_1340:
	s_andn2_b64 vcc, exec, s[26:27]
	s_waitcnt lgkmcnt(0)
	s_barrier
	s_cbranch_vccnz .LBB0_1300
	s_mov_b32 s23, s75
	s_lshl_b64 s[22:23], s[22:23], 12
	s_add_u32 s0, s14, s22
	v_or_b32_e32 v0, s66, v109
	s_addc_u32 s26, s15, s23
	s_lshl_b64 s[22:23], s[24:25], 1
	v_mad_u64_u32 v[42:43], s[24:25], v0, s79, v[108:109]
	ds_read_b128 v[26:29], v42
	s_add_u32 s22, s0, s22
	s_addc_u32 s23, s26, s23
	s_mov_b32 s0, 0x1e800000
	s_waitcnt lgkmcnt(0)
	v_sub_f32_e32 v39, v53, v29
	v_sub_f32_e32 v38, v52, v28
	v_sub_f32_e32 v41, v51, v27
	v_sub_f32_e32 v40, v50, v26
	ds_read_b128 v[26:29], v42 offset:64
	v_mov_b32_e32 v30, v39
	s_waitcnt lgkmcnt(0)
	v_sub_f32_e32 v37, v47, v27
	v_sub_f32_e32 v35, v49, v29
	v_sub_f32_e32 v34, v48, v28
	v_sub_f32_e32 v36, v46, v26
	v_mov_b32_e32 v28, v41
	v_mov_b32_e32 v29, v37
	v_mov_b32_e32 v26, v40
	v_mov_b32_e32 v27, v36
	v_pk_mul_f32 v[28:29], v[28:29], v[28:29]
	v_mov_b32_e32 v31, v35
	v_pk_fma_f32 v[26:27], v[26:27], v[26:27], v[28:29]
	v_mov_b32_e32 v28, v38
	v_mov_b32_e32 v29, v34
	v_pk_mul_f32 v[30:31], v[30:31], v[30:31]
	s_nop 0
	v_pk_fma_f32 v[28:29], v[28:29], v[28:29], v[30:31]
	s_nop 0
	v_pk_add_f32 v[44:45], v[26:27], v[28:29]
	ds_read_b128 v[26:29], v42 offset:128
	s_waitcnt lgkmcnt(0)
	v_sub_f32_e32 v31, v23, v27
	v_sub_f32_e32 v30, v22, v26
	v_sub_f32_e32 v33, v25, v29
	v_sub_f32_e32 v32, v24, v28
	v_pk_mul_f32 v[22:23], v[32:33], v[32:33]
	v_pk_mul_f32 v[24:25], v[30:31], v[30:31]
	s_nop 0
	v_pk_mov_b32 v[26:27], v[24:25], v[22:23] op_sel:[1,0]
	v_mov_b32_e32 v25, v23
	v_pk_add_f32 v[46:47], v[26:27], v[24:25]
	ds_read_b128 v[22:25], v42 offset:192
	s_waitcnt lgkmcnt(0)
	v_sub_f32_e32 v27, v19, v23
	v_sub_f32_e32 v26, v18, v22
	v_sub_f32_e32 v29, v21, v25
	v_sub_f32_e32 v28, v20, v24
	ds_read_b128 v[18:21], v42 offset:256
	s_waitcnt lgkmcnt(0)
	v_sub_f32_e32 v25, v15, v19
	v_sub_f32_e32 v24, v14, v18
	v_sub_f32_e32 v23, v17, v21
	v_sub_f32_e32 v22, v16, v20
	v_mul_f32_e32 v0, v24, v24
	v_mul_f32_e32 v18, v25, v25
	v_pk_add_f32 v[14:15], v[44:45], v[44:45] op_sel:[0,1] op_sel_hi:[1,0]
	v_pk_add_f32 v[16:17], v[46:47], v[46:47] op_sel:[0,1] op_sel_hi:[1,0]
	v_mov_b32_e32 v15, v0
	v_mov_b32_e32 v17, v18
	v_mul_f32_e32 v0, v27, v27
	v_mul_f32_e32 v19, v22, v22
	v_pk_add_f32 v[14:15], v[14:15], v[16:17]
	v_pk_fma_f32 v[16:17], v[26:27], v[26:27], v[0:1] op_sel_hi:[1,1,0]
	v_mul_f32_e32 v0, v29, v29
	v_mul_f32_e32 v20, v23, v23
	v_mov_b32_e32 v17, v19
	v_pk_fma_f32 v[18:19], v[28:29], v[28:29], v[0:1] op_sel_hi:[1,1,0]
	s_nop 0
	v_mov_b32_e32 v19, v20
	v_pk_add_f32 v[16:17], v[16:17], v[18:19]
	s_nop 0
	v_pk_add_f32 v[44:45], v[14:15], v[16:17]
	ds_read_b128 v[14:17], v42 offset:320
	s_waitcnt lgkmcnt(0)
	v_sub_f32_e32 v19, v11, v15
	v_sub_f32_e32 v18, v10, v14
	v_sub_f32_e32 v21, v13, v17
	v_sub_f32_e32 v20, v12, v16
	v_pk_mul_f32 v[10:11], v[20:21], v[20:21]
	v_pk_mul_f32 v[12:13], v[18:19], v[18:19]
	s_nop 0
	v_pk_mov_b32 v[14:15], v[12:13], v[10:11] op_sel:[1,0]
	v_mov_b32_e32 v13, v11
	v_pk_add_f32 v[46:47], v[14:15], v[12:13]
	ds_read_b128 v[10:13], v42 offset:384
	s_waitcnt lgkmcnt(0)
	v_sub_f32_e32 v15, v7, v11
	v_sub_f32_e32 v14, v6, v10
	v_sub_f32_e32 v17, v9, v13
	v_sub_f32_e32 v16, v8, v12
	ds_read_b128 v[8:11], v42 offset:448
	s_waitcnt lgkmcnt(0)
	v_sub_f32_e32 v9, v3, v9
	v_sub_f32_e32 v8, v2, v8
	v_pk_add_f32 v[2:3], v[44:45], v[44:45] op_sel:[0,1] op_sel_hi:[1,0]
	v_sub_f32_e32 v7, v5, v11
	v_sub_f32_e32 v6, v4, v10
	v_mul_f32_e32 v0, v8, v8
	v_mul_f32_e32 v10, v9, v9
	v_pk_add_f32 v[4:5], v[46:47], v[46:47] op_sel:[0,1] op_sel_hi:[1,0]
	v_mov_b32_e32 v3, v0
	v_mov_b32_e32 v5, v10
	v_mul_f32_e32 v0, v15, v15
	v_mul_f32_e32 v11, v6, v6
	v_pk_add_f32 v[2:3], v[2:3], v[4:5]
	v_pk_fma_f32 v[4:5], v[14:15], v[14:15], v[0:1] op_sel_hi:[1,1,0]
	v_mul_f32_e32 v0, v17, v17
	v_mul_f32_e32 v12, v7, v7
	v_mov_b32_e32 v5, v11
	v_pk_fma_f32 v[10:11], v[16:17], v[16:17], v[0:1] op_sel_hi:[1,1,0]
	s_nop 0
	v_mov_b32_e32 v11, v12
	v_pk_add_f32 v[4:5], v[4:5], v[10:11]
	s_nop 0
	v_pk_add_f32 v[2:3], v[2:3], v[4:5]
	s_nop 0
	v_add_f32_e32 v0, v2, v3
	ds_bpermute_b32 v2, v125, v0
	s_waitcnt lgkmcnt(0)
	v_add_f32_e32 v0, v0, v2
	ds_bpermute_b32 v2, v126, v0
	s_waitcnt lgkmcnt(0)
	v_add_f32_e32 v0, v0, v2
	v_fmamk_f32 v0, v0, 0x3c000000, v226
	v_cmp_gt_f32_e32 vcc, s97, v0
	v_mul_f32_e32 v2, 0x4b800000, v0
	s_nop 0
	v_cndmask_b32_e32 v0, v0, v2, vcc
	v_rsq_f32_e32 v0, v0
	s_nop 0
	v_mul_f32_e32 v2, 0x45800000, v0
	v_cndmask_b32_e32 v0, v0, v2, vcc
	v_sub_f32_e32 v2, 1.0, v177
	v_mul_f32_e32 v12, v2, v0
	v_lshl_or_b32 v0, s61, 16, v128
	v_pk_mul_f32 v[4:5], v[40:41], v[12:13] op_sel_hi:[1,0]
	v_lshl_add_u64 v[2:3], s[22:23], 0, v[0:1]
	v_lshlrev_b32_e32 v0, 1, v106
	v_lshl_add_u64 v[2:3], v[2:3], 0, v[0:1]
	v_pk_mul_f32 v[38:39], v[38:39], v[12:13] op_sel_hi:[1,0]
	s_mov_b64 s[22:23], 0x1e800400
	v_lshl_add_u64 v[10:11], v[2:3], 0, s[22:23]
	v_add_co_u32_e32 v2, vcc, s0, v2
	v_pk_mul_f32 v[36:37], v[36:37], v[12:13] op_sel_hi:[1,0]
	s_nop 0
	v_addc_co_u32_e32 v3, vcc, 0, v3, vcc
	v_pk_mul_f32 v[34:35], v[34:35], v[12:13] op_sel_hi:[1,0]
	v_pk_mul_f32 v[30:31], v[30:31], v[12:13] op_sel_hi:[1,0]
	v_pk_mul_f32 v[32:33], v[32:33], v[12:13] op_sel_hi:[1,0]
	v_pk_mul_f32 v[26:27], v[26:27], v[12:13] op_sel_hi:[1,0]
	v_pk_mul_f32 v[28:29], v[28:29], v[12:13] op_sel_hi:[1,0]
	v_pk_mul_f32 v[24:25], v[24:25], v[12:13] op_sel_hi:[1,0]
	v_pk_mul_f32 v[22:23], v[22:23], v[12:13] op_sel_hi:[1,0]
	v_pk_mul_f32 v[18:19], v[18:19], v[12:13] op_sel_hi:[1,0]
	v_pk_mul_f32 v[20:21], v[20:21], v[12:13] op_sel_hi:[1,0]
	v_pk_mul_f32 v[14:15], v[14:15], v[12:13] op_sel_hi:[1,0]
	v_pk_mul_f32 v[16:17], v[16:17], v[12:13] op_sel_hi:[1,0]
	v_pk_mul_f32 v[8:9], v[8:9], v[12:13] op_sel_hi:[1,0]
	v_pk_mul_f32 v[6:7], v[6:7], v[12:13] op_sel_hi:[1,0]
	s_waitcnt vmcnt(0)
	v_pk_mul_f32 v[4:5], v[160:161], v[4:5]
	s_nop 0
	v_bfe_u32 v0, v4, 16, 1
	v_add3_u32 v0, v4, v0, s84
	v_bfe_u32 v4, v5, 16, 1
	v_pk_mul_f32 v[38:39], v[162:163], v[38:39]
	v_lshrrev_b32_e32 v0, 16, v0
	v_add3_u32 v4, v5, v4, s84
	v_and_or_b32 v4, v4, s85, v0
	v_bfe_u32 v0, v38, 16, 1
	v_add3_u32 v0, v38, v0, s84
	v_bfe_u32 v5, v39, 16, 1
	v_lshrrev_b32_e32 v0, 16, v0
	v_add3_u32 v5, v39, v5, s84
	v_and_or_b32 v5, v5, s85, v0
	global_store_dwordx2 v[2:3], v[4:5], off offset:1024
	v_pk_mul_f32 v[2:3], v[164:165], v[36:37]
	s_nop 0
	v_bfe_u32 v0, v2, 16, 1
	v_add3_u32 v0, v2, v0, s84
	v_bfe_u32 v2, v3, 16, 1
	v_pk_mul_f32 v[4:5], v[166:167], v[34:35]
	v_lshrrev_b32_e32 v0, 16, v0
	v_add3_u32 v2, v3, v2, s84
	v_and_or_b32 v2, v2, s85, v0
	v_bfe_u32 v0, v4, 16, 1
	v_add3_u32 v0, v4, v0, s84
	v_bfe_u32 v3, v5, 16, 1
	v_lshrrev_b32_e32 v0, 16, v0
	v_add3_u32 v3, v5, v3, s84
	v_and_or_b32 v3, v3, s85, v0
	global_store_dwordx2 v[10:11], v[2:3], off offset:32
	v_pk_mul_f32 v[2:3], v[168:169], v[30:31]
	s_nop 0
	v_bfe_u32 v0, v2, 16, 1
	v_add3_u32 v0, v2, v0, s84
	v_bfe_u32 v2, v3, 16, 1
	v_pk_mul_f32 v[4:5], v[170:171], v[32:33]
	v_lshrrev_b32_e32 v0, 16, v0
	v_add3_u32 v2, v3, v2, s84
	v_and_or_b32 v2, v2, s85, v0
	v_bfe_u32 v0, v4, 16, 1
	v_add3_u32 v0, v4, v0, s84
	v_bfe_u32 v3, v5, 16, 1
	v_lshrrev_b32_e32 v0, 16, v0
	v_add3_u32 v3, v5, v3, s84
	v_and_or_b32 v3, v3, s85, v0
	global_store_dwordx2 v[10:11], v[2:3], off offset:64
	v_pk_mul_f32 v[2:3], v[172:173], v[26:27]
	s_nop 0
	v_bfe_u32 v0, v2, 16, 1
	v_add3_u32 v0, v2, v0, s84
	v_bfe_u32 v2, v3, 16, 1
	v_pk_mul_f32 v[4:5], v[174:175], v[28:29]
	v_lshrrev_b32_e32 v0, 16, v0
	v_add3_u32 v2, v3, v2, s84
	v_and_or_b32 v2, v2, s85, v0
	v_bfe_u32 v0, v4, 16, 1
	v_add3_u32 v0, v4, v0, s84
	v_bfe_u32 v3, v5, 16, 1
	v_lshrrev_b32_e32 v0, 16, v0
	v_add3_u32 v3, v5, v3, s84
	v_and_or_b32 v3, v3, s85, v0
	global_store_dwordx2 v[10:11], v[2:3], off offset:96
	v_pk_mul_f32 v[2:3], v[204:205], v[24:25]
	s_nop 0
	v_bfe_u32 v0, v2, 16, 1
	v_add3_u32 v0, v2, v0, s84
	v_bfe_u32 v2, v3, 16, 1
	v_pk_mul_f32 v[4:5], v[206:207], v[22:23]
	v_lshrrev_b32_e32 v0, 16, v0
	v_add3_u32 v2, v3, v2, s84
	v_and_or_b32 v2, v2, s85, v0
	v_bfe_u32 v0, v4, 16, 1
	v_add3_u32 v0, v4, v0, s84
	v_bfe_u32 v3, v5, 16, 1
	v_lshrrev_b32_e32 v0, 16, v0
	v_add3_u32 v3, v5, v3, s84
	v_and_or_b32 v3, v3, s85, v0
	global_store_dwordx2 v[10:11], v[2:3], off offset:128
	v_pk_mul_f32 v[2:3], v[208:209], v[18:19]
	s_nop 0
	v_bfe_u32 v0, v2, 16, 1
	v_add3_u32 v0, v2, v0, s84
	v_bfe_u32 v2, v3, 16, 1
	v_pk_mul_f32 v[4:5], v[210:211], v[20:21]
	v_lshrrev_b32_e32 v0, 16, v0
	v_add3_u32 v2, v3, v2, s84
	v_and_or_b32 v2, v2, s85, v0
	v_bfe_u32 v0, v4, 16, 1
	v_add3_u32 v0, v4, v0, s84
	v_bfe_u32 v3, v5, 16, 1
	v_lshrrev_b32_e32 v0, 16, v0
	v_add3_u32 v3, v5, v3, s84
	v_and_or_b32 v3, v3, s85, v0
	global_store_dwordx2 v[10:11], v[2:3], off offset:160
	v_pk_mul_f32 v[2:3], v[212:213], v[14:15]
	s_nop 0
	v_bfe_u32 v0, v2, 16, 1
	v_add3_u32 v0, v2, v0, s84
	v_bfe_u32 v2, v3, 16, 1
	v_pk_mul_f32 v[4:5], v[214:215], v[16:17]
	v_lshrrev_b32_e32 v0, 16, v0
	v_add3_u32 v2, v3, v2, s84
	v_and_or_b32 v2, v2, s85, v0
	v_bfe_u32 v0, v4, 16, 1
	v_add3_u32 v0, v4, v0, s84
	v_bfe_u32 v3, v5, 16, 1
	v_lshrrev_b32_e32 v0, 16, v0
	v_add3_u32 v3, v5, v3, s84
	v_and_or_b32 v3, v3, s85, v0
	global_store_dwordx2 v[10:11], v[2:3], off offset:192
	v_pk_mul_f32 v[2:3], v[216:217], v[8:9]
	s_nop 0
	v_bfe_u32 v0, v2, 16, 1
	v_add3_u32 v0, v2, v0, s84
	v_bfe_u32 v2, v3, 16, 1
	v_pk_mul_f32 v[4:5], v[218:219], v[6:7]
	v_lshrrev_b32_e32 v0, 16, v0
	v_add3_u32 v2, v3, v2, s84
	v_and_or_b32 v2, v2, s85, v0
	v_bfe_u32 v0, v4, 16, 1
	v_add3_u32 v0, v4, v0, s84
	v_bfe_u32 v3, v5, 16, 1
	v_lshrrev_b32_e32 v0, 16, v0
	v_add3_u32 v3, v5, v3, s84
	v_and_or_b32 v3, v3, s85, v0
	global_store_dwordx2 v[10:11], v[2:3], off offset:224
	s_branch .LBB0_1300
